# up main loop: two 32-MFMA compute phases per K-tile instead of four 16-MFMA phases (half the barriers), six LDS-DMA pieces in the second memory phase
# speedup vs baseline: 1.0111x; 1.0035x over previous
.LBB0_104:
	s_add_u32 s2, s34, 0xfffc2080
	s_addc_u32 s3, s35, -1
	s_add_i32 s12, 0, 0x10000
	v_add_u32_e32 v110, s12, v179
	ds_read_b128 v[98:101], v110
	ds_read_b128 v[102:105], v110 offset:1024
	ds_read_b128 v[106:109], v110 offset:2048
	ds_read_b128 v[110:113], v110 offset:3072
	s_cmp_eq_u32 s53, 12
	s_cselect_b32 s49, s97, s3
	s_cselect_b32 s48, s96, s2
	s_cselect_b32 s3, s1, s52
	s_cselect_b32 s2, s23, s51
	v_lshl_add_u64 v[174:175], s[34:35], 0, v[170:171]
	s_add_i32 m0, s85, 0xc000
	ds_read_b128 v[114:117], v184
	ds_read_b128 v[118:121], v184 offset:1024
	ds_read_b128 v[122:125], v184 offset:2048
	ds_read_b128 v[126:129], v184 offset:3072
	ds_read_b128 v[186:189], v184 offset:4096
	ds_read_b128 v[190:193], v184 offset:5120
	ds_read_b128 v[194:197], v184 offset:6144
	ds_read_b128 v[198:201], v184 offset:7168
	global_load_lds_dwordx4 v[174:175], off
	v_lshl_add_u64 v[174:175], s[34:35], 0, v[172:173]
	s_add_i32 m0, s85, 0xe000
	s_nop 0
	global_load_lds_dwordx4 v[174:175], off
	s_waitcnt lgkmcnt(8)
	s_add_i32 s54, 0, 0x14000
	v_add_u32_e32 v174, s54, v179
	s_add_i32 s12, s12, s78
	ds_read_b128 v[226:229], v174
	ds_read_b128 v[230:233], v174 offset:1024
	ds_read_b128 v[234:237], v174 offset:2048
	ds_read_b128 v[242:245], v174 offset:3072
	s_barrier
	s_waitcnt lgkmcnt(0)
	s_waitcnt lgkmcnt(0)
	v_mfma_f32_16x16x32_bf16 v[158:161], v[98:101], v[114:117], v[158:161]
	v_mfma_f32_16x16x32_bf16 v[154:157], v[106:109], v[114:117], v[154:157]
	v_mfma_f32_16x16x32_bf16 v[150:153], v[98:101], v[122:125], v[150:153]
	v_mfma_f32_16x16x32_bf16 v[146:149], v[106:109], v[122:125], v[146:149]
	v_mfma_f32_16x16x32_bf16 v[142:145], v[98:101], v[186:189], v[142:145]
	v_mfma_f32_16x16x32_bf16 v[138:141], v[106:109], v[186:189], v[138:141]
	v_mfma_f32_16x16x32_bf16 v[134:137], v[98:101], v[194:197], v[134:137]
	v_mfma_f32_16x16x32_bf16 v[130:133], v[106:109], v[194:197], v[130:133]
	v_mfma_f32_16x16x32_bf16 v[158:161], v[102:105], v[118:121], v[158:161]
	v_mfma_f32_16x16x32_bf16 v[154:157], v[110:113], v[118:121], v[154:157]
	v_mfma_f32_16x16x32_bf16 v[150:153], v[102:105], v[126:129], v[150:153]
	v_mfma_f32_16x16x32_bf16 v[146:149], v[110:113], v[126:129], v[146:149]
	v_mfma_f32_16x16x32_bf16 v[142:145], v[102:105], v[190:193], v[142:145]
	v_mfma_f32_16x16x32_bf16 v[138:141], v[110:113], v[190:193], v[138:141]
	v_mfma_f32_16x16x32_bf16 v[134:137], v[102:105], v[198:201], v[134:137]
	v_mfma_f32_16x16x32_bf16 v[130:133], v[110:113], v[198:201], v[130:133]
	s_waitcnt lgkmcnt(0)
	s_waitcnt lgkmcnt(0)
	v_mfma_f32_16x16x32_bf16 v[62:65], v[226:229], v[114:117], v[62:65]
	v_mfma_f32_16x16x32_bf16 v[58:61], v[234:237], v[114:117], v[58:61]
	v_mfma_f32_16x16x32_bf16 v[54:57], v[226:229], v[122:125], v[54:57]
	v_mfma_f32_16x16x32_bf16 v[50:53], v[234:237], v[122:125], v[50:53]
	v_mfma_f32_16x16x32_bf16 v[46:49], v[226:229], v[186:189], v[46:49]
	v_mfma_f32_16x16x32_bf16 v[42:45], v[234:237], v[186:189], v[42:45]
	v_mfma_f32_16x16x32_bf16 v[38:41], v[226:229], v[194:197], v[38:41]
	v_mfma_f32_16x16x32_bf16 v[34:37], v[234:237], v[194:197], v[34:37]
	v_mfma_f32_16x16x32_bf16 v[62:65], v[230:233], v[118:121], v[62:65]
	v_mfma_f32_16x16x32_bf16 v[58:61], v[242:245], v[118:121], v[58:61]
	v_mfma_f32_16x16x32_bf16 v[54:57], v[230:233], v[126:129], v[54:57]
	v_mfma_f32_16x16x32_bf16 v[50:53], v[242:245], v[126:129], v[50:53]
	v_mfma_f32_16x16x32_bf16 v[46:49], v[230:233], v[190:193], v[46:49]
	v_mfma_f32_16x16x32_bf16 v[42:45], v[242:245], v[190:193], v[42:45]
	v_mfma_f32_16x16x32_bf16 v[38:41], v[230:233], v[198:201], v[38:41]
	v_mfma_f32_16x16x32_bf16 v[34:37], v[242:245], v[198:201], v[34:37]
	s_mov_b32 m0, s85
	v_lshl_add_u64 v[248:249], s[48:49], 0, v[162:163]
	s_barrier
	ds_read_b128 v[114:117], v184 offset:16384
	ds_read_b128 v[118:121], v184 offset:17408
	ds_read_b128 v[122:125], v184 offset:18432
	ds_read_b128 v[126:129], v184 offset:19456
	ds_read_b128 v[186:189], v184 offset:20480
	ds_read_b128 v[190:193], v184 offset:21504
	ds_read_b128 v[194:197], v184 offset:22528
	ds_read_b128 v[198:201], v184 offset:23552
	global_load_lds_dwordx4 v[248:249], off
	v_lshl_add_u64 v[250:251], s[48:49], 0, v[164:165]
	s_mov_b32 m0, s82
	s_nop 0
	global_load_lds_dwordx4 v[250:251], off
	v_lshl_add_u64 v[174:175], s[2:3], 0, v[0:1]
	s_mov_b32 m0, s12
	v_lshl_add_u64 v[246:247], s[2:3], 0, v[166:167]
	global_load_lds_dwordx4 v[174:175], off
	s_add_i32 m0, s12, 0x2000
	s_nop 0
	global_load_lds_dwordx4 v[246:247], off
	s_add_u32 s12, s2, 0x40000
	s_addc_u32 s13, s3, 0
	s_add_i32 s54, s54, s78
	v_lshl_add_u64 v[174:175], s[12:13], 0, v[0:1]
	s_mov_b32 m0, s54
	s_nop 0
	global_load_lds_dwordx4 v[174:175], off
	v_lshl_add_u64 v[174:175], s[12:13], 0, v[166:167]
	s_add_i32 m0, s54, 0x2000
	s_nop 0
	global_load_lds_dwordx4 v[174:175], off
	s_waitcnt vmcnt(6)
	s_barrier
	s_waitcnt lgkmcnt(0)
	s_waitcnt lgkmcnt(0)
	v_mfma_f32_16x16x32_bf16 v[94:97], v[98:101], v[114:117], v[94:97]
	v_mfma_f32_16x16x32_bf16 v[90:93], v[106:109], v[114:117], v[90:93]
	v_mfma_f32_16x16x32_bf16 v[86:89], v[98:101], v[122:125], v[86:89]
	v_mfma_f32_16x16x32_bf16 v[82:85], v[106:109], v[122:125], v[82:85]
	v_mfma_f32_16x16x32_bf16 v[78:81], v[98:101], v[186:189], v[78:81]
	v_mfma_f32_16x16x32_bf16 v[74:77], v[106:109], v[186:189], v[74:77]
	v_mfma_f32_16x16x32_bf16 v[70:73], v[98:101], v[194:197], v[70:73]
	v_mfma_f32_16x16x32_bf16 v[66:69], v[106:109], v[194:197], v[66:69]
	v_mfma_f32_16x16x32_bf16 v[94:97], v[102:105], v[118:121], v[94:97]
	v_mfma_f32_16x16x32_bf16 v[90:93], v[110:113], v[118:121], v[90:93]
	v_mfma_f32_16x16x32_bf16 v[86:89], v[102:105], v[126:129], v[86:89]
	v_mfma_f32_16x16x32_bf16 v[82:85], v[110:113], v[126:129], v[82:85]
	v_mfma_f32_16x16x32_bf16 v[78:81], v[102:105], v[190:193], v[78:81]
	v_mfma_f32_16x16x32_bf16 v[74:77], v[110:113], v[190:193], v[74:77]
	v_mfma_f32_16x16x32_bf16 v[70:73], v[102:105], v[198:201], v[70:73]
	v_mfma_f32_16x16x32_bf16 v[66:69], v[110:113], v[198:201], v[66:69]
	v_mfma_f32_16x16x32_bf16 v[30:33], v[226:229], v[114:117], v[30:33]
	v_mfma_f32_16x16x32_bf16 v[26:29], v[234:237], v[114:117], v[26:29]
	v_mfma_f32_16x16x32_bf16 v[22:25], v[226:229], v[122:125], v[22:25]
	v_mfma_f32_16x16x32_bf16 v[18:21], v[234:237], v[122:125], v[18:21]
	v_mfma_f32_16x16x32_bf16 v[14:17], v[226:229], v[186:189], v[14:17]
	v_mfma_f32_16x16x32_bf16 v[10:13], v[234:237], v[186:189], v[10:13]
	v_mfma_f32_16x16x32_bf16 v[6:9], v[226:229], v[194:197], v[6:9]
	v_mfma_f32_16x16x32_bf16 v[2:5], v[234:237], v[194:197], v[2:5]
	v_mfma_f32_16x16x32_bf16 v[30:33], v[230:233], v[118:121], v[30:33]
	v_mfma_f32_16x16x32_bf16 v[26:29], v[242:245], v[118:121], v[26:29]
	v_mfma_f32_16x16x32_bf16 v[22:25], v[230:233], v[126:129], v[22:25]
	v_mfma_f32_16x16x32_bf16 v[18:21], v[242:245], v[126:129], v[18:21]
	v_mfma_f32_16x16x32_bf16 v[14:17], v[230:233], v[190:193], v[14:17]
	v_mfma_f32_16x16x32_bf16 v[10:13], v[242:245], v[190:193], v[10:13]
	v_mfma_f32_16x16x32_bf16 v[6:9], v[230:233], v[198:201], v[6:9]
	v_mfma_f32_16x16x32_bf16 v[2:5], v[242:245], v[198:201], v[2:5]
	s_add_i32 s54, 0, 0x18000
	v_add_u32_e32 v110, s54, v179
	s_barrier
	ds_read_b128 v[98:101], v110
	ds_read_b128 v[102:105], v110 offset:1024
	ds_read_b128 v[106:109], v110 offset:2048
	ds_read_b128 v[110:113], v110 offset:3072
	s_add_u32 s12, s48, 0x3e000
	s_addc_u32 s13, s49, 0
	s_mov_b32 m0, s89
	v_lshl_add_u64 v[226:227], s[12:13], 0, v[162:163]
	ds_read_b128 v[114:117], v184 offset:32768
	ds_read_b128 v[118:121], v184 offset:33792
	ds_read_b128 v[122:125], v184 offset:34816
	ds_read_b128 v[126:129], v184 offset:35840
	ds_read_b128 v[186:189], v184 offset:36864
	ds_read_b128 v[190:193], v184 offset:37888
	ds_read_b128 v[194:197], v184 offset:38912
	ds_read_b128 v[198:201], v184 offset:39936
	global_load_lds_dwordx4 v[226:227], off
	v_lshl_add_u64 v[226:227], s[12:13], 0, v[164:165]
	s_mov_b32 m0, s91
	s_nop 0
	global_load_lds_dwordx4 v[226:227], off
	s_waitcnt lgkmcnt(8)
	s_add_i32 s12, 0, 0x1c000
	s_add_i32 s13, s54, s78
	v_add_u32_e32 v242, s12, v179
	ds_read_b128 v[226:229], v242
	ds_read_b128 v[230:233], v242 offset:1024
	ds_read_b128 v[234:237], v242 offset:2048
	ds_read_b128 v[242:245], v242 offset:3072
	s_barrier
	s_waitcnt lgkmcnt(0)
	s_waitcnt lgkmcnt(0)
	v_mfma_f32_16x16x32_bf16 v[158:161], v[98:101], v[114:117], v[158:161]
	v_mfma_f32_16x16x32_bf16 v[154:157], v[106:109], v[114:117], v[154:157]
	v_mfma_f32_16x16x32_bf16 v[150:153], v[98:101], v[122:125], v[150:153]
	v_mfma_f32_16x16x32_bf16 v[146:149], v[106:109], v[122:125], v[146:149]
	v_mfma_f32_16x16x32_bf16 v[142:145], v[98:101], v[186:189], v[142:145]
	v_mfma_f32_16x16x32_bf16 v[138:141], v[106:109], v[186:189], v[138:141]
	v_mfma_f32_16x16x32_bf16 v[134:137], v[98:101], v[194:197], v[134:137]
	v_mfma_f32_16x16x32_bf16 v[130:133], v[106:109], v[194:197], v[130:133]
	v_mfma_f32_16x16x32_bf16 v[158:161], v[102:105], v[118:121], v[158:161]
	v_mfma_f32_16x16x32_bf16 v[154:157], v[110:113], v[118:121], v[154:157]
	v_mfma_f32_16x16x32_bf16 v[150:153], v[102:105], v[126:129], v[150:153]
	v_mfma_f32_16x16x32_bf16 v[146:149], v[110:113], v[126:129], v[146:149]
	v_mfma_f32_16x16x32_bf16 v[142:145], v[102:105], v[190:193], v[142:145]
	v_mfma_f32_16x16x32_bf16 v[138:141], v[110:113], v[190:193], v[138:141]
	v_mfma_f32_16x16x32_bf16 v[134:137], v[102:105], v[198:201], v[134:137]
	v_mfma_f32_16x16x32_bf16 v[130:133], v[110:113], v[198:201], v[130:133]
	s_waitcnt lgkmcnt(0)
	s_waitcnt lgkmcnt(0)
	v_mfma_f32_16x16x32_bf16 v[62:65], v[226:229], v[114:117], v[62:65]
	v_mfma_f32_16x16x32_bf16 v[58:61], v[234:237], v[114:117], v[58:61]
	v_mfma_f32_16x16x32_bf16 v[54:57], v[226:229], v[122:125], v[54:57]
	v_mfma_f32_16x16x32_bf16 v[50:53], v[234:237], v[122:125], v[50:53]
	v_mfma_f32_16x16x32_bf16 v[46:49], v[226:229], v[186:189], v[46:49]
	v_mfma_f32_16x16x32_bf16 v[42:45], v[234:237], v[186:189], v[42:45]
	v_mfma_f32_16x16x32_bf16 v[38:41], v[226:229], v[194:197], v[38:41]
	v_mfma_f32_16x16x32_bf16 v[34:37], v[234:237], v[194:197], v[34:37]
	v_mfma_f32_16x16x32_bf16 v[62:65], v[230:233], v[118:121], v[62:65]
	v_mfma_f32_16x16x32_bf16 v[58:61], v[242:245], v[118:121], v[58:61]
	v_mfma_f32_16x16x32_bf16 v[54:57], v[230:233], v[126:129], v[54:57]
	v_mfma_f32_16x16x32_bf16 v[50:53], v[242:245], v[126:129], v[50:53]
	v_mfma_f32_16x16x32_bf16 v[46:49], v[230:233], v[190:193], v[46:49]
	v_mfma_f32_16x16x32_bf16 v[42:45], v[242:245], v[190:193], v[42:45]
	v_mfma_f32_16x16x32_bf16 v[38:41], v[230:233], v[198:201], v[38:41]
	v_mfma_f32_16x16x32_bf16 v[34:37], v[242:245], v[198:201], v[34:37]
	s_mov_b32 m0, s79
	v_lshl_add_u64 v[174:175], v[248:249], 0, s[20:21]
	s_barrier
	ds_read_b128 v[114:117], v184 offset:49152
	ds_read_b128 v[118:121], v184 offset:50176
	ds_read_b128 v[122:125], v184 offset:51200
	ds_read_b128 v[126:129], v184 offset:52224
	ds_read_b128 v[186:189], v184 offset:53248
	ds_read_b128 v[190:193], v184 offset:54272
	ds_read_b128 v[194:197], v184 offset:55296
	ds_read_b128 v[198:201], v184 offset:56320
	global_load_lds_dwordx4 v[174:175], off
	v_lshl_add_u64 v[174:175], v[250:251], 0, s[20:21]
	s_mov_b32 m0, s87
	s_nop 0
	global_load_lds_dwordx4 v[174:175], off
	v_lshl_add_u64 v[174:175], s[2:3], 0, v[0:1]
	v_lshl_add_u64 v[174:175], v[174:175], 0, s[20:21]
	s_mov_b32 m0, s13
	s_nop 0
	global_load_lds_dwordx4 v[174:175], off
	v_lshl_add_u64 v[174:175], v[246:247], 0, s[20:21]
	s_add_i32 m0, s13, 0x2000
	s_nop 0
	global_load_lds_dwordx4 v[174:175], off
	s_add_u32 s2, s2, 0x40080
	s_addc_u32 s3, s3, 0
	s_add_i32 s12, s12, s78
	v_lshl_add_u64 v[174:175], s[2:3], 0, v[0:1]
	s_mov_b32 m0, s12
	s_nop 0
	global_load_lds_dwordx4 v[174:175], off
	v_lshl_add_u64 v[174:175], s[2:3], 0, v[166:167]
	s_add_i32 m0, s12, 0x2000
	s_nop 0
	global_load_lds_dwordx4 v[174:175], off
	s_waitcnt vmcnt(6)
	s_barrier
	s_waitcnt lgkmcnt(0)
	s_waitcnt lgkmcnt(0)
	v_mfma_f32_16x16x32_bf16 v[94:97], v[98:101], v[114:117], v[94:97]
	v_mfma_f32_16x16x32_bf16 v[90:93], v[106:109], v[114:117], v[90:93]
	v_mfma_f32_16x16x32_bf16 v[86:89], v[98:101], v[122:125], v[86:89]
	v_mfma_f32_16x16x32_bf16 v[82:85], v[106:109], v[122:125], v[82:85]
	v_mfma_f32_16x16x32_bf16 v[78:81], v[98:101], v[186:189], v[78:81]
	v_mfma_f32_16x16x32_bf16 v[74:77], v[106:109], v[186:189], v[74:77]
	v_mfma_f32_16x16x32_bf16 v[70:73], v[98:101], v[194:197], v[70:73]
	v_mfma_f32_16x16x32_bf16 v[66:69], v[106:109], v[194:197], v[66:69]
	v_mfma_f32_16x16x32_bf16 v[94:97], v[102:105], v[118:121], v[94:97]
	v_mfma_f32_16x16x32_bf16 v[90:93], v[110:113], v[118:121], v[90:93]
	v_mfma_f32_16x16x32_bf16 v[86:89], v[102:105], v[126:129], v[86:89]
	v_mfma_f32_16x16x32_bf16 v[82:85], v[110:113], v[126:129], v[82:85]
	v_mfma_f32_16x16x32_bf16 v[78:81], v[102:105], v[190:193], v[78:81]
	v_mfma_f32_16x16x32_bf16 v[74:77], v[110:113], v[190:193], v[74:77]
	v_mfma_f32_16x16x32_bf16 v[70:73], v[102:105], v[198:201], v[70:73]
	v_mfma_f32_16x16x32_bf16 v[66:69], v[110:113], v[198:201], v[66:69]
	v_mfma_f32_16x16x32_bf16 v[30:33], v[226:229], v[114:117], v[30:33]
	v_mfma_f32_16x16x32_bf16 v[26:29], v[234:237], v[114:117], v[26:29]
	v_mfma_f32_16x16x32_bf16 v[22:25], v[226:229], v[122:125], v[22:25]
	v_mfma_f32_16x16x32_bf16 v[18:21], v[234:237], v[122:125], v[18:21]
	v_mfma_f32_16x16x32_bf16 v[14:17], v[226:229], v[186:189], v[14:17]
	v_mfma_f32_16x16x32_bf16 v[10:13], v[234:237], v[186:189], v[10:13]
	v_mfma_f32_16x16x32_bf16 v[6:9], v[226:229], v[194:197], v[6:9]
	v_mfma_f32_16x16x32_bf16 v[2:5], v[234:237], v[194:197], v[2:5]
	v_mfma_f32_16x16x32_bf16 v[30:33], v[230:233], v[118:121], v[30:33]
	v_mfma_f32_16x16x32_bf16 v[26:29], v[242:245], v[118:121], v[26:29]
	v_mfma_f32_16x16x32_bf16 v[22:25], v[230:233], v[126:129], v[22:25]
	v_mfma_f32_16x16x32_bf16 v[18:21], v[242:245], v[126:129], v[18:21]
	v_mfma_f32_16x16x32_bf16 v[14:17], v[230:233], v[190:193], v[14:17]
	v_mfma_f32_16x16x32_bf16 v[10:13], v[242:245], v[190:193], v[10:13]
	v_mfma_f32_16x16x32_bf16 v[6:9], v[230:233], v[198:201], v[6:9]
	v_mfma_f32_16x16x32_bf16 v[2:5], v[242:245], v[198:201], v[2:5]
	s_add_i32 s53, s53, 2
	s_add_u32 s34, s34, 0x100
	s_addc_u32 s35, s35, 0
	s_add_u32 s51, s51, 0x100
	s_addc_u32 s52, s52, 0
	s_cmp_gt_u32 s53, 13
	s_barrier
	s_cbranch_scc0 .LBB0_104
	s_add_i32 s1, s50, 0xffffffbd
	s_cmpk_gt_i32 s50, 0x42
	s_cselect_b32 s1, s1, s50
	s_mul_i32 s23, s1, 0xf8
	s_cselect_b32 s2, 0x4000, 0
	s_cselect_b32 s3, 0x100, s37
	s_add_i32 s23, s23, s84
	v_add_u32_e32 v188, s88, v178
	s_mov_b32 s50, 0xbfb8aa3b
	s_mov_b32 s51, 0xbfb8aa3b
	ds_read_b128 v[126:129], v188
	ds_read_b128 v[122:125], v188 offset:128
	ds_read_b128 v[114:117], v188 offset:256
	ds_read_b128 v[118:121], v188 offset:384
	ds_read_b128 v[110:113], v188 offset:512
	ds_read_b128 v[106:109], v188 offset:640
	ds_read_b128 v[98:101], v188 offset:768
	ds_read_b128 v[102:105], v188 offset:896
	v_readlane_b32 s12, v252, 28
	v_readlane_b32 s13, v252, 29
	v_bfe_u32 v231, v202, 5, 1
	v_and_b32_e32 v174, 48, v180
	v_lshl_or_b32 v174, v231, 3, v174
	v_lshl_or_b32 v174, s0, 7, v174
	v_bfe_u32 v230, v202, 4, 1
	v_lshl_add_u32 v186, v177, 2, s23
	v_cmp_eq_u32_e32 vcc, 1, v230
	s_or_b64 s[52:53], s[42:43], vcc
	v_cmp_eq_u32_e32 vcc, 0, v230
	s_or_b64 s[54:55], s[44:45], vcc
	v_add_u32_e32 v186, v186, v230
	v_add_u32_e32 v187, s2, v186
	v_mul_u32_u24_e32 v187, 0x1600, v187
	v_lshl_add_u32 v187, v174, 1, v187
	s_waitcnt lgkmcnt(0)
	v_pk_fma_f32 v[190:191], v[158:159], v[122:123], v[118:119]
	v_pk_fma_f32 v[192:193], v[160:161], v[124:125], v[120:121]
	v_pk_fma_f32 v[194:195], v[154:155], v[106:107], v[102:103]
	v_pk_fma_f32 v[196:197], v[156:157], v[108:109], v[104:105]
	v_add_u32_e32 v230, 0, v186
	v_fmac_f32_dpp v190, v134, v126 row_ror:1 row_mask:0xf bank_mask:0xf
	v_fmac_f32_dpp v191, v135, v127 row_ror:1 row_mask:0xf bank_mask:0xf
	v_fmac_f32_dpp v192, v136, v128 row_ror:1 row_mask:0xf bank_mask:0xf
	v_fmac_f32_dpp v193, v137, v129 row_ror:1 row_mask:0xf bank_mask:0xf
	v_fmac_f32_dpp v194, v130, v110 row_ror:1 row_mask:0xf bank_mask:0xf
	v_fmac_f32_dpp v195, v131, v111 row_ror:1 row_mask:0xf bank_mask:0xf
	v_fmac_f32_dpp v196, v132, v112 row_ror:1 row_mask:0xf bank_mask:0xf
	v_fmac_f32_dpp v197, v133, v113 row_ror:1 row_mask:0xf bank_mask:0xf
	v_pk_fma_f32 v[190:191], v[150:151], v[114:115], v[190:191]
	v_pk_fma_f32 v[192:193], v[152:153], v[116:117], v[192:193]
	v_pk_fma_f32 v[194:195], v[146:147], v[98:99], v[194:195]
	v_pk_fma_f32 v[196:197], v[148:149], v[100:101], v[196:197]
	v_pk_mul_f32 v[198:199], v[190:191], s[50:51]
	v_pk_mul_f32 v[200:201], v[192:193], s[50:51]
	v_exp_f32_e32 v198, v198
	v_exp_f32_e32 v199, v199
	v_exp_f32_e32 v200, v200
	v_exp_f32_e32 v201, v201
	v_add_f32_e32 v198, 1.0, v198
	v_add_f32_e32 v199, 1.0, v199
	v_add_f32_e32 v200, 1.0, v200
	v_add_f32_e32 v201, 1.0, v201
	v_rcp_f32_e32 v198, v198
	v_rcp_f32_e32 v199, v199
	v_rcp_f32_e32 v200, v200
	v_rcp_f32_e32 v201, v201
	v_pk_mul_f32 v[190:191], v[190:191], v[198:199]
	v_pk_mul_f32 v[192:193], v[192:193], v[200:201]
	v_pk_mul_f32 v[190:191], v[190:191], v[194:195]
	v_pk_mul_f32 v[192:193], v[192:193], v[196:197]
	v_cvt_pk_bf16_f32 v232, v190, v191
	v_cvt_pk_bf16_f32 v233, v192, v193
	v_pk_fma_f32 v[190:191], v[150:151], v[122:123], v[118:119]
	v_pk_fma_f32 v[192:193], v[152:153], v[124:125], v[120:121]
	v_pk_fma_f32 v[194:195], v[146:147], v[106:107], v[102:103]
	v_pk_fma_f32 v[196:197], v[148:149], v[108:109], v[104:105]
	v_pk_fma_f32 v[190:191], v[158:159], v[126:127], v[190:191]
	v_pk_fma_f32 v[192:193], v[160:161], v[128:129], v[192:193]
	v_pk_fma_f32 v[194:195], v[154:155], v[110:111], v[194:195]
	v_pk_fma_f32 v[196:197], v[156:157], v[112:113], v[196:197]
	v_pk_fma_f32 v[190:191], v[142:143], v[114:115], v[190:191]
	v_pk_fma_f32 v[192:193], v[144:145], v[116:117], v[192:193]
	v_pk_fma_f32 v[194:195], v[138:139], v[98:99], v[194:195]
	v_pk_fma_f32 v[196:197], v[140:141], v[100:101], v[196:197]
	v_pk_mul_f32 v[198:199], v[190:191], s[50:51]
	v_pk_mul_f32 v[200:201], v[192:193], s[50:51]
	v_exp_f32_e32 v198, v198
	v_exp_f32_e32 v199, v199
	v_exp_f32_e32 v200, v200
	v_exp_f32_e32 v201, v201
	v_add_f32_e32 v198, 1.0, v198
	v_add_f32_e32 v199, 1.0, v199
	v_add_f32_e32 v200, 1.0, v200
	v_add_f32_e32 v201, 1.0, v201
	v_rcp_f32_e32 v198, v198
	v_rcp_f32_e32 v199, v199
	v_rcp_f32_e32 v200, v200
	v_rcp_f32_e32 v201, v201
	v_pk_mul_f32 v[190:191], v[190:191], v[198:199]
	v_pk_mul_f32 v[192:193], v[192:193], v[200:201]
	v_pk_mul_f32 v[190:191], v[190:191], v[194:195]
	v_pk_mul_f32 v[192:193], v[192:193], v[196:197]
	v_cvt_pk_bf16_f32 v234, v190, v191
	v_cvt_pk_bf16_f32 v235, v192, v193
	v_cmp_gt_i32_e32 vcc, s3, v230
	s_and_b64 vcc, vcc, s[52:53]
	s_nop 0
	v_permlane16_swap_b32_e32 v232, v234
	v_permlane16_swap_b32_e32 v233, v235
	s_and_saveexec_b64 s[0:1], vcc
	global_store_dwordx4 v187, v[232:235], s[12:13]
	s_mov_b64 exec, s[0:1]
	v_pk_fma_f32 v[190:191], v[142:143], v[122:123], v[118:119]
	v_pk_fma_f32 v[192:193], v[144:145], v[124:125], v[120:121]
	v_pk_fma_f32 v[194:195], v[138:139], v[106:107], v[102:103]
	v_pk_fma_f32 v[196:197], v[140:141], v[108:109], v[104:105]
	v_add_u32_e32 v230, 2, v186
	v_add_u32_e32 v231, 0x2c00, v187
	v_pk_fma_f32 v[190:191], v[150:151], v[126:127], v[190:191]
	v_pk_fma_f32 v[192:193], v[152:153], v[128:129], v[192:193]
	v_pk_fma_f32 v[194:195], v[146:147], v[110:111], v[194:195]
	v_pk_fma_f32 v[196:197], v[148:149], v[112:113], v[196:197]
	v_pk_fma_f32 v[190:191], v[134:135], v[114:115], v[190:191]
	v_pk_fma_f32 v[192:193], v[136:137], v[116:117], v[192:193]
	v_pk_fma_f32 v[194:195], v[130:131], v[98:99], v[194:195]
	v_pk_fma_f32 v[196:197], v[132:133], v[100:101], v[196:197]
	v_pk_mul_f32 v[198:199], v[190:191], s[50:51]
	v_pk_mul_f32 v[200:201], v[192:193], s[50:51]
	v_exp_f32_e32 v198, v198
	v_exp_f32_e32 v199, v199
	v_exp_f32_e32 v200, v200
	v_exp_f32_e32 v201, v201
	v_add_f32_e32 v198, 1.0, v198
	v_add_f32_e32 v199, 1.0, v199
	v_add_f32_e32 v200, 1.0, v200
	v_add_f32_e32 v201, 1.0, v201
	v_rcp_f32_e32 v198, v198
	v_rcp_f32_e32 v199, v199
	v_rcp_f32_e32 v200, v200
	v_rcp_f32_e32 v201, v201
	v_pk_mul_f32 v[190:191], v[190:191], v[198:199]
	v_pk_mul_f32 v[192:193], v[192:193], v[200:201]
	v_pk_mul_f32 v[190:191], v[190:191], v[194:195]
	v_pk_mul_f32 v[192:193], v[192:193], v[196:197]
	v_cvt_pk_bf16_f32 v232, v190, v191
	v_cvt_pk_bf16_f32 v233, v192, v193
	v_pk_fma_f32 v[190:191], v[134:135], v[122:123], v[118:119]
	v_pk_fma_f32 v[192:193], v[136:137], v[124:125], v[120:121]
	v_pk_fma_f32 v[194:195], v[130:131], v[106:107], v[102:103]
	v_pk_fma_f32 v[196:197], v[132:133], v[108:109], v[104:105]
	v_pk_fma_f32 v[190:191], v[142:143], v[126:127], v[190:191]
	v_pk_fma_f32 v[192:193], v[144:145], v[128:129], v[192:193]
	v_pk_fma_f32 v[194:195], v[138:139], v[110:111], v[194:195]
	v_pk_fma_f32 v[196:197], v[140:141], v[112:113], v[196:197]
	v_fmac_f32_dpp v190, v158, v114 row_ror:15 row_mask:0xf bank_mask:0xf
	v_fmac_f32_dpp v191, v159, v115 row_ror:15 row_mask:0xf bank_mask:0xf
	v_fmac_f32_dpp v192, v160, v116 row_ror:15 row_mask:0xf bank_mask:0xf
	v_fmac_f32_dpp v193, v161, v117 row_ror:15 row_mask:0xf bank_mask:0xf
	v_fmac_f32_dpp v194, v154, v98 row_ror:15 row_mask:0xf bank_mask:0xf
	v_fmac_f32_dpp v195, v155, v99 row_ror:15 row_mask:0xf bank_mask:0xf
	v_fmac_f32_dpp v196, v156, v100 row_ror:15 row_mask:0xf bank_mask:0xf
	v_fmac_f32_dpp v197, v157, v101 row_ror:15 row_mask:0xf bank_mask:0xf
	v_pk_mul_f32 v[198:199], v[190:191], s[50:51]
	v_pk_mul_f32 v[200:201], v[192:193], s[50:51]
	v_exp_f32_e32 v198, v198
	v_exp_f32_e32 v199, v199
	v_exp_f32_e32 v200, v200
	v_exp_f32_e32 v201, v201
	v_add_f32_e32 v198, 1.0, v198
	v_add_f32_e32 v199, 1.0, v199
	v_add_f32_e32 v200, 1.0, v200
	v_add_f32_e32 v201, 1.0, v201
	v_rcp_f32_e32 v198, v198
	v_rcp_f32_e32 v199, v199
	v_rcp_f32_e32 v200, v200
	v_rcp_f32_e32 v201, v201
	v_pk_mul_f32 v[190:191], v[190:191], v[198:199]
	v_pk_mul_f32 v[192:193], v[192:193], v[200:201]
	v_pk_mul_f32 v[190:191], v[190:191], v[194:195]
	v_pk_mul_f32 v[192:193], v[192:193], v[196:197]
	v_cvt_pk_bf16_f32 v234, v190, v191
	v_cvt_pk_bf16_f32 v235, v192, v193
	v_cmp_gt_i32_e32 vcc, s3, v230
	s_and_b64 vcc, vcc, s[54:55]
	s_nop 0
	v_permlane16_swap_b32_e32 v232, v234
	v_permlane16_swap_b32_e32 v233, v235
	s_and_saveexec_b64 s[0:1], vcc
	global_store_dwordx4 v231, v[232:235], s[12:13]
	s_mov_b64 exec, s[0:1]
	ds_read_b128 v[130:133], v188 offset:64
	ds_read_b128 v[134:137], v188 offset:192
	ds_read_b128 v[138:141], v188 offset:320
	ds_read_b128 v[142:145], v188 offset:448
	ds_read_b128 v[146:149], v188 offset:576
	ds_read_b128 v[150:153], v188 offset:704
	ds_read_b128 v[154:157], v188 offset:832
	ds_read_b128 v[158:161], v188 offset:960
	v_pk_fma_f32 v[190:191], v[94:95], v[122:123], v[118:119]
	v_pk_fma_f32 v[192:193], v[96:97], v[124:125], v[120:121]
	v_pk_fma_f32 v[194:195], v[90:91], v[106:107], v[102:103]
	v_pk_fma_f32 v[196:197], v[92:93], v[108:109], v[104:105]
	v_add_u32_e32 v230, 0x7c, v186
	v_add_u32_e32 v231, 0xaa800, v187
	v_fmac_f32_dpp v190, v70, v126 row_ror:1 row_mask:0xf bank_mask:0xf
	v_fmac_f32_dpp v191, v71, v127 row_ror:1 row_mask:0xf bank_mask:0xf
	v_fmac_f32_dpp v192, v72, v128 row_ror:1 row_mask:0xf bank_mask:0xf
	v_fmac_f32_dpp v193, v73, v129 row_ror:1 row_mask:0xf bank_mask:0xf
	v_fmac_f32_dpp v194, v66, v110 row_ror:1 row_mask:0xf bank_mask:0xf
	v_fmac_f32_dpp v195, v67, v111 row_ror:1 row_mask:0xf bank_mask:0xf
	v_fmac_f32_dpp v196, v68, v112 row_ror:1 row_mask:0xf bank_mask:0xf
	v_fmac_f32_dpp v197, v69, v113 row_ror:1 row_mask:0xf bank_mask:0xf
	v_pk_fma_f32 v[190:191], v[86:87], v[114:115], v[190:191]
	v_pk_fma_f32 v[192:193], v[88:89], v[116:117], v[192:193]
	v_pk_fma_f32 v[194:195], v[82:83], v[98:99], v[194:195]
	v_pk_fma_f32 v[196:197], v[84:85], v[100:101], v[196:197]
	v_pk_mul_f32 v[198:199], v[190:191], s[50:51]
	v_pk_mul_f32 v[200:201], v[192:193], s[50:51]
	v_exp_f32_e32 v198, v198
	v_exp_f32_e32 v199, v199
	v_exp_f32_e32 v200, v200
	v_exp_f32_e32 v201, v201
	v_add_f32_e32 v198, 1.0, v198
	v_add_f32_e32 v199, 1.0, v199
	v_add_f32_e32 v200, 1.0, v200
	v_add_f32_e32 v201, 1.0, v201
	v_rcp_f32_e32 v198, v198
	v_rcp_f32_e32 v199, v199
	v_rcp_f32_e32 v200, v200
	v_rcp_f32_e32 v201, v201
	v_pk_mul_f32 v[190:191], v[190:191], v[198:199]
	v_pk_mul_f32 v[192:193], v[192:193], v[200:201]
	v_pk_mul_f32 v[190:191], v[190:191], v[194:195]
	v_pk_mul_f32 v[192:193], v[192:193], v[196:197]
	v_cvt_pk_bf16_f32 v232, v190, v191
	v_cvt_pk_bf16_f32 v233, v192, v193
	v_pk_fma_f32 v[190:191], v[86:87], v[122:123], v[118:119]
	v_pk_fma_f32 v[192:193], v[88:89], v[124:125], v[120:121]
	v_pk_fma_f32 v[194:195], v[82:83], v[106:107], v[102:103]
	v_pk_fma_f32 v[196:197], v[84:85], v[108:109], v[104:105]
	v_pk_fma_f32 v[190:191], v[94:95], v[126:127], v[190:191]
	v_pk_fma_f32 v[192:193], v[96:97], v[128:129], v[192:193]
	v_pk_fma_f32 v[194:195], v[90:91], v[110:111], v[194:195]
	v_pk_fma_f32 v[196:197], v[92:93], v[112:113], v[196:197]
	v_pk_fma_f32 v[190:191], v[78:79], v[114:115], v[190:191]
	v_pk_fma_f32 v[192:193], v[80:81], v[116:117], v[192:193]
	v_pk_fma_f32 v[194:195], v[74:75], v[98:99], v[194:195]
	v_pk_fma_f32 v[196:197], v[76:77], v[100:101], v[196:197]
	v_pk_mul_f32 v[198:199], v[190:191], s[50:51]
	v_pk_mul_f32 v[200:201], v[192:193], s[50:51]
	v_exp_f32_e32 v198, v198
	v_exp_f32_e32 v199, v199
	v_exp_f32_e32 v200, v200
	v_exp_f32_e32 v201, v201
	v_add_f32_e32 v198, 1.0, v198
	v_add_f32_e32 v199, 1.0, v199
	v_add_f32_e32 v200, 1.0, v200
	v_add_f32_e32 v201, 1.0, v201
	v_rcp_f32_e32 v198, v198
	v_rcp_f32_e32 v199, v199
	v_rcp_f32_e32 v200, v200
	v_rcp_f32_e32 v201, v201
	v_pk_mul_f32 v[190:191], v[190:191], v[198:199]
	v_pk_mul_f32 v[192:193], v[192:193], v[200:201]
	v_pk_mul_f32 v[190:191], v[190:191], v[194:195]
	v_pk_mul_f32 v[192:193], v[192:193], v[196:197]
	v_cvt_pk_bf16_f32 v234, v190, v191
	v_cvt_pk_bf16_f32 v235, v192, v193
	v_cmp_gt_i32_e32 vcc, s3, v230
	s_and_b64 vcc, vcc, s[52:53]
	s_nop 0
	v_permlane16_swap_b32_e32 v232, v234
	v_permlane16_swap_b32_e32 v233, v235
	s_and_saveexec_b64 s[0:1], vcc
	global_store_dwordx4 v231, v[232:235], s[12:13]
	s_mov_b64 exec, s[0:1]
	v_pk_fma_f32 v[190:191], v[78:79], v[122:123], v[118:119]
	v_pk_fma_f32 v[192:193], v[80:81], v[124:125], v[120:121]
	v_pk_fma_f32 v[194:195], v[74:75], v[106:107], v[102:103]
	v_pk_fma_f32 v[196:197], v[76:77], v[108:109], v[104:105]
	v_add_u32_e32 v230, 0x7e, v186
	v_add_u32_e32 v231, 0xad400, v187
	v_pk_fma_f32 v[190:191], v[86:87], v[126:127], v[190:191]
	v_pk_fma_f32 v[192:193], v[88:89], v[128:129], v[192:193]
	v_pk_fma_f32 v[194:195], v[82:83], v[110:111], v[194:195]
	v_pk_fma_f32 v[196:197], v[84:85], v[112:113], v[196:197]
	v_pk_fma_f32 v[190:191], v[70:71], v[114:115], v[190:191]
	v_pk_fma_f32 v[192:193], v[72:73], v[116:117], v[192:193]
	v_pk_fma_f32 v[194:195], v[66:67], v[98:99], v[194:195]
	v_pk_fma_f32 v[196:197], v[68:69], v[100:101], v[196:197]
	v_pk_mul_f32 v[198:199], v[190:191], s[50:51]
	v_pk_mul_f32 v[200:201], v[192:193], s[50:51]
	v_exp_f32_e32 v198, v198
	v_exp_f32_e32 v199, v199
	v_exp_f32_e32 v200, v200
	v_exp_f32_e32 v201, v201
	v_add_f32_e32 v198, 1.0, v198
	v_add_f32_e32 v199, 1.0, v199
	v_add_f32_e32 v200, 1.0, v200
	v_add_f32_e32 v201, 1.0, v201
	v_rcp_f32_e32 v198, v198
	v_rcp_f32_e32 v199, v199
	v_rcp_f32_e32 v200, v200
	v_rcp_f32_e32 v201, v201
	v_pk_mul_f32 v[190:191], v[190:191], v[198:199]
	v_pk_mul_f32 v[192:193], v[192:193], v[200:201]
	v_pk_mul_f32 v[190:191], v[190:191], v[194:195]
	v_pk_mul_f32 v[192:193], v[192:193], v[196:197]
	v_cvt_pk_bf16_f32 v232, v190, v191
	v_cvt_pk_bf16_f32 v233, v192, v193
	v_pk_fma_f32 v[190:191], v[70:71], v[122:123], v[118:119]
	v_pk_fma_f32 v[192:193], v[72:73], v[124:125], v[120:121]
	v_pk_fma_f32 v[194:195], v[66:67], v[106:107], v[102:103]
	v_pk_fma_f32 v[196:197], v[68:69], v[108:109], v[104:105]
	v_pk_fma_f32 v[190:191], v[78:79], v[126:127], v[190:191]
	v_pk_fma_f32 v[192:193], v[80:81], v[128:129], v[192:193]
	v_pk_fma_f32 v[194:195], v[74:75], v[110:111], v[194:195]
	v_pk_fma_f32 v[196:197], v[76:77], v[112:113], v[196:197]
	v_fmac_f32_dpp v190, v94, v114 row_ror:15 row_mask:0xf bank_mask:0xf
	v_fmac_f32_dpp v191, v95, v115 row_ror:15 row_mask:0xf bank_mask:0xf
	v_fmac_f32_dpp v192, v96, v116 row_ror:15 row_mask:0xf bank_mask:0xf
	v_fmac_f32_dpp v193, v97, v117 row_ror:15 row_mask:0xf bank_mask:0xf
	v_fmac_f32_dpp v194, v90, v98 row_ror:15 row_mask:0xf bank_mask:0xf
	v_fmac_f32_dpp v195, v91, v99 row_ror:15 row_mask:0xf bank_mask:0xf
	v_fmac_f32_dpp v196, v92, v100 row_ror:15 row_mask:0xf bank_mask:0xf
	v_fmac_f32_dpp v197, v93, v101 row_ror:15 row_mask:0xf bank_mask:0xf
	v_pk_mul_f32 v[198:199], v[190:191], s[50:51]
	v_pk_mul_f32 v[200:201], v[192:193], s[50:51]
	v_exp_f32_e32 v198, v198
	v_exp_f32_e32 v199, v199
	v_exp_f32_e32 v200, v200
	v_exp_f32_e32 v201, v201
	v_add_f32_e32 v198, 1.0, v198
	v_add_f32_e32 v199, 1.0, v199
	v_add_f32_e32 v200, 1.0, v200
	v_add_f32_e32 v201, 1.0, v201
	v_rcp_f32_e32 v198, v198
	v_rcp_f32_e32 v199, v199
	v_rcp_f32_e32 v200, v200
	v_rcp_f32_e32 v201, v201
	v_pk_mul_f32 v[190:191], v[190:191], v[198:199]
	v_pk_mul_f32 v[192:193], v[192:193], v[200:201]
	v_pk_mul_f32 v[190:191], v[190:191], v[194:195]
	v_pk_mul_f32 v[192:193], v[192:193], v[196:197]
	v_cvt_pk_bf16_f32 v234, v190, v191
	v_cvt_pk_bf16_f32 v235, v192, v193
	v_cmp_gt_i32_e32 vcc, s3, v230
	s_and_b64 vcc, vcc, s[54:55]
	s_nop 0
	v_permlane16_swap_b32_e32 v232, v234
	v_permlane16_swap_b32_e32 v233, v235
	s_and_saveexec_b64 s[0:1], vcc
	global_store_dwordx4 v231, v[232:235], s[12:13]
	s_mov_b64 exec, s[0:1]
	s_waitcnt lgkmcnt(0)
	v_pk_fma_f32 v[190:191], v[62:63], v[134:135], v[142:143]
	v_pk_fma_f32 v[192:193], v[64:65], v[136:137], v[144:145]
	v_pk_fma_f32 v[194:195], v[58:59], v[150:151], v[158:159]
	v_pk_fma_f32 v[196:197], v[60:61], v[152:153], v[160:161]
	v_add_u32_e32 v230, 0, v186
	v_fmac_f32_dpp v190, v38, v130 row_ror:1 row_mask:0xf bank_mask:0xf
	v_fmac_f32_dpp v191, v39, v131 row_ror:1 row_mask:0xf bank_mask:0xf
	v_fmac_f32_dpp v192, v40, v132 row_ror:1 row_mask:0xf bank_mask:0xf
	v_fmac_f32_dpp v193, v41, v133 row_ror:1 row_mask:0xf bank_mask:0xf
	v_fmac_f32_dpp v194, v34, v146 row_ror:1 row_mask:0xf bank_mask:0xf
	v_fmac_f32_dpp v195, v35, v147 row_ror:1 row_mask:0xf bank_mask:0xf
	v_fmac_f32_dpp v196, v36, v148 row_ror:1 row_mask:0xf bank_mask:0xf
	v_fmac_f32_dpp v197, v37, v149 row_ror:1 row_mask:0xf bank_mask:0xf
	v_pk_fma_f32 v[190:191], v[54:55], v[138:139], v[190:191]
	v_pk_fma_f32 v[192:193], v[56:57], v[140:141], v[192:193]
	v_pk_fma_f32 v[194:195], v[50:51], v[154:155], v[194:195]
	v_pk_fma_f32 v[196:197], v[52:53], v[156:157], v[196:197]
	v_pk_mul_f32 v[198:199], v[190:191], s[50:51]
	v_pk_mul_f32 v[200:201], v[192:193], s[50:51]
	v_exp_f32_e32 v198, v198
	v_exp_f32_e32 v199, v199
	v_exp_f32_e32 v200, v200
	v_exp_f32_e32 v201, v201
	v_add_f32_e32 v198, 1.0, v198
	v_add_f32_e32 v199, 1.0, v199
	v_add_f32_e32 v200, 1.0, v200
	v_add_f32_e32 v201, 1.0, v201
	v_rcp_f32_e32 v198, v198
	v_rcp_f32_e32 v199, v199
	v_rcp_f32_e32 v200, v200
	v_rcp_f32_e32 v201, v201
	v_pk_mul_f32 v[190:191], v[190:191], v[198:199]
	v_pk_mul_f32 v[192:193], v[192:193], v[200:201]
	v_pk_mul_f32 v[190:191], v[190:191], v[194:195]
	v_pk_mul_f32 v[192:193], v[192:193], v[196:197]
	v_cvt_pk_bf16_f32 v232, v190, v191
	v_cvt_pk_bf16_f32 v233, v192, v193
	v_pk_fma_f32 v[190:191], v[54:55], v[134:135], v[142:143]
	v_pk_fma_f32 v[192:193], v[56:57], v[136:137], v[144:145]
	v_pk_fma_f32 v[194:195], v[50:51], v[150:151], v[158:159]
	v_pk_fma_f32 v[196:197], v[52:53], v[152:153], v[160:161]
	v_pk_fma_f32 v[190:191], v[62:63], v[130:131], v[190:191]
	v_pk_fma_f32 v[192:193], v[64:65], v[132:133], v[192:193]
	v_pk_fma_f32 v[194:195], v[58:59], v[146:147], v[194:195]
	v_pk_fma_f32 v[196:197], v[60:61], v[148:149], v[196:197]
	v_pk_fma_f32 v[190:191], v[46:47], v[138:139], v[190:191]
	v_pk_fma_f32 v[192:193], v[48:49], v[140:141], v[192:193]
	v_pk_fma_f32 v[194:195], v[42:43], v[154:155], v[194:195]
	v_pk_fma_f32 v[196:197], v[44:45], v[156:157], v[196:197]
	v_pk_mul_f32 v[198:199], v[190:191], s[50:51]
	v_pk_mul_f32 v[200:201], v[192:193], s[50:51]
	v_exp_f32_e32 v198, v198
	v_exp_f32_e32 v199, v199
	v_exp_f32_e32 v200, v200
	v_exp_f32_e32 v201, v201
	v_add_f32_e32 v198, 1.0, v198
	v_add_f32_e32 v199, 1.0, v199
	v_add_f32_e32 v200, 1.0, v200
	v_add_f32_e32 v201, 1.0, v201
	v_rcp_f32_e32 v198, v198
	v_rcp_f32_e32 v199, v199
	v_rcp_f32_e32 v200, v200
	v_rcp_f32_e32 v201, v201
	v_pk_mul_f32 v[190:191], v[190:191], v[198:199]
	v_pk_mul_f32 v[192:193], v[192:193], v[200:201]
	v_pk_mul_f32 v[190:191], v[190:191], v[194:195]
	v_pk_mul_f32 v[192:193], v[192:193], v[196:197]
	v_cvt_pk_bf16_f32 v234, v190, v191
	v_cvt_pk_bf16_f32 v235, v192, v193
	v_cmp_gt_i32_e32 vcc, s3, v230
	s_and_b64 vcc, vcc, s[52:53]
	s_nop 0
	v_permlane16_swap_b32_e32 v232, v234
	v_permlane16_swap_b32_e32 v233, v235
	s_and_saveexec_b64 s[0:1], vcc
	global_store_dwordx4 v187, v[232:235], s[12:13] offset:128
	s_mov_b64 exec, s[0:1]
	v_pk_fma_f32 v[190:191], v[46:47], v[134:135], v[142:143]
	v_pk_fma_f32 v[192:193], v[48:49], v[136:137], v[144:145]
	v_pk_fma_f32 v[194:195], v[42:43], v[150:151], v[158:159]
	v_pk_fma_f32 v[196:197], v[44:45], v[152:153], v[160:161]
	v_add_u32_e32 v230, 2, v186
	v_add_u32_e32 v231, 0x2c00, v187
	v_pk_fma_f32 v[190:191], v[54:55], v[130:131], v[190:191]
	v_pk_fma_f32 v[192:193], v[56:57], v[132:133], v[192:193]
	v_pk_fma_f32 v[194:195], v[50:51], v[146:147], v[194:195]
	v_pk_fma_f32 v[196:197], v[52:53], v[148:149], v[196:197]
	v_pk_fma_f32 v[190:191], v[38:39], v[138:139], v[190:191]
	v_pk_fma_f32 v[192:193], v[40:41], v[140:141], v[192:193]
	v_pk_fma_f32 v[194:195], v[34:35], v[154:155], v[194:195]
	v_pk_fma_f32 v[196:197], v[36:37], v[156:157], v[196:197]
	v_pk_mul_f32 v[198:199], v[190:191], s[50:51]
	v_pk_mul_f32 v[200:201], v[192:193], s[50:51]
	v_exp_f32_e32 v198, v198
	v_exp_f32_e32 v199, v199
	v_exp_f32_e32 v200, v200
	v_exp_f32_e32 v201, v201
	v_add_f32_e32 v198, 1.0, v198
	v_add_f32_e32 v199, 1.0, v199
	v_add_f32_e32 v200, 1.0, v200
	v_add_f32_e32 v201, 1.0, v201
	v_rcp_f32_e32 v198, v198
	v_rcp_f32_e32 v199, v199
	v_rcp_f32_e32 v200, v200
	v_rcp_f32_e32 v201, v201
	v_pk_mul_f32 v[190:191], v[190:191], v[198:199]
	v_pk_mul_f32 v[192:193], v[192:193], v[200:201]
	v_pk_mul_f32 v[190:191], v[190:191], v[194:195]
	v_pk_mul_f32 v[192:193], v[192:193], v[196:197]
	v_cvt_pk_bf16_f32 v232, v190, v191
	v_cvt_pk_bf16_f32 v233, v192, v193
	v_pk_fma_f32 v[190:191], v[38:39], v[134:135], v[142:143]
	v_pk_fma_f32 v[192:193], v[40:41], v[136:137], v[144:145]
	v_pk_fma_f32 v[194:195], v[34:35], v[150:151], v[158:159]
	v_pk_fma_f32 v[196:197], v[36:37], v[152:153], v[160:161]
	v_pk_fma_f32 v[190:191], v[46:47], v[130:131], v[190:191]
	v_pk_fma_f32 v[192:193], v[48:49], v[132:133], v[192:193]
	v_pk_fma_f32 v[194:195], v[42:43], v[146:147], v[194:195]
	v_pk_fma_f32 v[196:197], v[44:45], v[148:149], v[196:197]
	v_fmac_f32_dpp v190, v62, v138 row_ror:15 row_mask:0xf bank_mask:0xf
	v_fmac_f32_dpp v191, v63, v139 row_ror:15 row_mask:0xf bank_mask:0xf
	v_fmac_f32_dpp v192, v64, v140 row_ror:15 row_mask:0xf bank_mask:0xf
	v_fmac_f32_dpp v193, v65, v141 row_ror:15 row_mask:0xf bank_mask:0xf
	v_fmac_f32_dpp v194, v58, v154 row_ror:15 row_mask:0xf bank_mask:0xf
	v_fmac_f32_dpp v195, v59, v155 row_ror:15 row_mask:0xf bank_mask:0xf
	v_fmac_f32_dpp v196, v60, v156 row_ror:15 row_mask:0xf bank_mask:0xf
	v_fmac_f32_dpp v197, v61, v157 row_ror:15 row_mask:0xf bank_mask:0xf
	v_pk_mul_f32 v[198:199], v[190:191], s[50:51]
	v_pk_mul_f32 v[200:201], v[192:193], s[50:51]
	v_exp_f32_e32 v198, v198
	v_exp_f32_e32 v199, v199
	v_exp_f32_e32 v200, v200
	v_exp_f32_e32 v201, v201
	v_add_f32_e32 v198, 1.0, v198
	v_add_f32_e32 v199, 1.0, v199
	v_add_f32_e32 v200, 1.0, v200
	v_add_f32_e32 v201, 1.0, v201
	v_rcp_f32_e32 v198, v198
	v_rcp_f32_e32 v199, v199
	v_rcp_f32_e32 v200, v200
	v_rcp_f32_e32 v201, v201
	v_pk_mul_f32 v[190:191], v[190:191], v[198:199]
	v_pk_mul_f32 v[192:193], v[192:193], v[200:201]
	v_pk_mul_f32 v[190:191], v[190:191], v[194:195]
	v_pk_mul_f32 v[192:193], v[192:193], v[196:197]
	v_cvt_pk_bf16_f32 v234, v190, v191
	v_cvt_pk_bf16_f32 v235, v192, v193
	v_cmp_gt_i32_e32 vcc, s3, v230
	s_and_b64 vcc, vcc, s[54:55]
	s_nop 0
	v_permlane16_swap_b32_e32 v232, v234
	v_permlane16_swap_b32_e32 v233, v235
	s_and_saveexec_b64 s[0:1], vcc
	global_store_dwordx4 v231, v[232:235], s[12:13] offset:128
	s_mov_b64 exec, s[0:1]
	v_pk_fma_f32 v[190:191], v[30:31], v[134:135], v[142:143]
	v_pk_fma_f32 v[192:193], v[32:33], v[136:137], v[144:145]
	v_pk_fma_f32 v[194:195], v[26:27], v[150:151], v[158:159]
	v_pk_fma_f32 v[196:197], v[28:29], v[152:153], v[160:161]
	v_add_u32_e32 v230, 0x7c, v186
	v_add_u32_e32 v231, 0xaa800, v187
	v_fmac_f32_dpp v190, v6, v130 row_ror:1 row_mask:0xf bank_mask:0xf
	v_fmac_f32_dpp v191, v7, v131 row_ror:1 row_mask:0xf bank_mask:0xf
	v_fmac_f32_dpp v192, v8, v132 row_ror:1 row_mask:0xf bank_mask:0xf
	v_fmac_f32_dpp v193, v9, v133 row_ror:1 row_mask:0xf bank_mask:0xf
	v_fmac_f32_dpp v194, v2, v146 row_ror:1 row_mask:0xf bank_mask:0xf
	v_fmac_f32_dpp v195, v3, v147 row_ror:1 row_mask:0xf bank_mask:0xf
	v_fmac_f32_dpp v196, v4, v148 row_ror:1 row_mask:0xf bank_mask:0xf
	v_fmac_f32_dpp v197, v5, v149 row_ror:1 row_mask:0xf bank_mask:0xf
	v_pk_fma_f32 v[190:191], v[22:23], v[138:139], v[190:191]
	v_pk_fma_f32 v[192:193], v[24:25], v[140:141], v[192:193]
	v_pk_fma_f32 v[194:195], v[18:19], v[154:155], v[194:195]
	v_pk_fma_f32 v[196:197], v[20:21], v[156:157], v[196:197]
	v_pk_mul_f32 v[198:199], v[190:191], s[50:51]
	v_pk_mul_f32 v[200:201], v[192:193], s[50:51]
	v_exp_f32_e32 v198, v198
	v_exp_f32_e32 v199, v199
	v_exp_f32_e32 v200, v200
	v_exp_f32_e32 v201, v201
	v_add_f32_e32 v198, 1.0, v198
	v_add_f32_e32 v199, 1.0, v199
	v_add_f32_e32 v200, 1.0, v200
	v_add_f32_e32 v201, 1.0, v201
	v_rcp_f32_e32 v198, v198
	v_rcp_f32_e32 v199, v199
	v_rcp_f32_e32 v200, v200
	v_rcp_f32_e32 v201, v201
	v_pk_mul_f32 v[190:191], v[190:191], v[198:199]
	v_pk_mul_f32 v[192:193], v[192:193], v[200:201]
	v_pk_mul_f32 v[190:191], v[190:191], v[194:195]
	v_pk_mul_f32 v[192:193], v[192:193], v[196:197]
	v_cvt_pk_bf16_f32 v232, v190, v191
	v_cvt_pk_bf16_f32 v233, v192, v193
	v_pk_fma_f32 v[190:191], v[22:23], v[134:135], v[142:143]
	v_pk_fma_f32 v[192:193], v[24:25], v[136:137], v[144:145]
	v_pk_fma_f32 v[194:195], v[18:19], v[150:151], v[158:159]
	v_pk_fma_f32 v[196:197], v[20:21], v[152:153], v[160:161]
	v_pk_fma_f32 v[190:191], v[30:31], v[130:131], v[190:191]
	v_pk_fma_f32 v[192:193], v[32:33], v[132:133], v[192:193]
	v_pk_fma_f32 v[194:195], v[26:27], v[146:147], v[194:195]
	v_pk_fma_f32 v[196:197], v[28:29], v[148:149], v[196:197]
	v_pk_fma_f32 v[190:191], v[14:15], v[138:139], v[190:191]
	v_pk_fma_f32 v[192:193], v[16:17], v[140:141], v[192:193]
	v_pk_fma_f32 v[194:195], v[10:11], v[154:155], v[194:195]
	v_pk_fma_f32 v[196:197], v[12:13], v[156:157], v[196:197]
	v_pk_mul_f32 v[198:199], v[190:191], s[50:51]
	v_pk_mul_f32 v[200:201], v[192:193], s[50:51]
	v_exp_f32_e32 v198, v198
	v_exp_f32_e32 v199, v199
	v_exp_f32_e32 v200, v200
	v_exp_f32_e32 v201, v201
	v_add_f32_e32 v198, 1.0, v198
	v_add_f32_e32 v199, 1.0, v199
	v_add_f32_e32 v200, 1.0, v200
	v_add_f32_e32 v201, 1.0, v201
	v_rcp_f32_e32 v198, v198
	v_rcp_f32_e32 v199, v199
	v_rcp_f32_e32 v200, v200
	v_rcp_f32_e32 v201, v201
	v_pk_mul_f32 v[190:191], v[190:191], v[198:199]
	v_pk_mul_f32 v[192:193], v[192:193], v[200:201]
	v_pk_mul_f32 v[190:191], v[190:191], v[194:195]
	v_pk_mul_f32 v[192:193], v[192:193], v[196:197]
	v_cvt_pk_bf16_f32 v234, v190, v191
	v_cvt_pk_bf16_f32 v235, v192, v193
	v_cmp_gt_i32_e32 vcc, s3, v230
	s_and_b64 vcc, vcc, s[52:53]
	s_nop 0
	v_permlane16_swap_b32_e32 v232, v234
	v_permlane16_swap_b32_e32 v233, v235
	s_and_saveexec_b64 s[0:1], vcc
	global_store_dwordx4 v231, v[232:235], s[12:13] offset:128
	s_mov_b64 exec, s[0:1]
	v_pk_fma_f32 v[190:191], v[14:15], v[134:135], v[142:143]
	v_pk_fma_f32 v[192:193], v[16:17], v[136:137], v[144:145]
	v_pk_fma_f32 v[194:195], v[10:11], v[150:151], v[158:159]
	v_pk_fma_f32 v[196:197], v[12:13], v[152:153], v[160:161]
	v_add_u32_e32 v230, 0x7e, v186
	v_add_u32_e32 v231, 0xad400, v187
	v_pk_fma_f32 v[190:191], v[22:23], v[130:131], v[190:191]
	v_pk_fma_f32 v[192:193], v[24:25], v[132:133], v[192:193]
	v_pk_fma_f32 v[194:195], v[18:19], v[146:147], v[194:195]
	v_pk_fma_f32 v[196:197], v[20:21], v[148:149], v[196:197]
	v_pk_fma_f32 v[190:191], v[6:7], v[138:139], v[190:191]
	v_pk_fma_f32 v[192:193], v[8:9], v[140:141], v[192:193]
	v_pk_fma_f32 v[194:195], v[2:3], v[154:155], v[194:195]
	v_pk_fma_f32 v[196:197], v[4:5], v[156:157], v[196:197]
	v_pk_mul_f32 v[198:199], v[190:191], s[50:51]
	v_pk_mul_f32 v[200:201], v[192:193], s[50:51]
	v_exp_f32_e32 v198, v198
	v_exp_f32_e32 v199, v199
	v_exp_f32_e32 v200, v200
	v_exp_f32_e32 v201, v201
	v_add_f32_e32 v198, 1.0, v198
	v_add_f32_e32 v199, 1.0, v199
	v_add_f32_e32 v200, 1.0, v200
	v_add_f32_e32 v201, 1.0, v201
	v_rcp_f32_e32 v198, v198
	v_rcp_f32_e32 v199, v199
	v_rcp_f32_e32 v200, v200
	v_rcp_f32_e32 v201, v201
	v_pk_mul_f32 v[190:191], v[190:191], v[198:199]
	v_pk_mul_f32 v[192:193], v[192:193], v[200:201]
	v_pk_mul_f32 v[190:191], v[190:191], v[194:195]
	v_pk_mul_f32 v[192:193], v[192:193], v[196:197]
	v_cvt_pk_bf16_f32 v232, v190, v191
	v_cvt_pk_bf16_f32 v233, v192, v193
	v_pk_fma_f32 v[190:191], v[6:7], v[134:135], v[142:143]
	v_pk_fma_f32 v[192:193], v[8:9], v[136:137], v[144:145]
	v_pk_fma_f32 v[194:195], v[2:3], v[150:151], v[158:159]
	v_pk_fma_f32 v[196:197], v[4:5], v[152:153], v[160:161]
	v_pk_fma_f32 v[190:191], v[14:15], v[130:131], v[190:191]
	v_pk_fma_f32 v[192:193], v[16:17], v[132:133], v[192:193]
	v_pk_fma_f32 v[194:195], v[10:11], v[146:147], v[194:195]
	v_pk_fma_f32 v[196:197], v[12:13], v[148:149], v[196:197]
	v_fmac_f32_dpp v190, v30, v138 row_ror:15 row_mask:0xf bank_mask:0xf
	v_fmac_f32_dpp v191, v31, v139 row_ror:15 row_mask:0xf bank_mask:0xf
	v_fmac_f32_dpp v192, v32, v140 row_ror:15 row_mask:0xf bank_mask:0xf
	v_fmac_f32_dpp v193, v33, v141 row_ror:15 row_mask:0xf bank_mask:0xf
	v_fmac_f32_dpp v194, v26, v154 row_ror:15 row_mask:0xf bank_mask:0xf
	v_fmac_f32_dpp v195, v27, v155 row_ror:15 row_mask:0xf bank_mask:0xf
	v_fmac_f32_dpp v196, v28, v156 row_ror:15 row_mask:0xf bank_mask:0xf
	v_fmac_f32_dpp v197, v29, v157 row_ror:15 row_mask:0xf bank_mask:0xf
	v_pk_mul_f32 v[198:199], v[190:191], s[50:51]
	v_pk_mul_f32 v[200:201], v[192:193], s[50:51]
	v_exp_f32_e32 v198, v198
	v_exp_f32_e32 v199, v199
	v_exp_f32_e32 v200, v200
	v_exp_f32_e32 v201, v201
	v_add_f32_e32 v198, 1.0, v198
	v_add_f32_e32 v199, 1.0, v199
	v_add_f32_e32 v200, 1.0, v200
	v_add_f32_e32 v201, 1.0, v201
	v_rcp_f32_e32 v198, v198
	v_rcp_f32_e32 v199, v199
	v_rcp_f32_e32 v200, v200
	v_rcp_f32_e32 v201, v201
	v_pk_mul_f32 v[190:191], v[190:191], v[198:199]
	v_pk_mul_f32 v[192:193], v[192:193], v[200:201]
	v_pk_mul_f32 v[190:191], v[190:191], v[194:195]
	v_pk_mul_f32 v[192:193], v[192:193], v[196:197]
	v_cvt_pk_bf16_f32 v234, v190, v191
	v_cvt_pk_bf16_f32 v235, v192, v193
	v_cmp_gt_i32_e32 vcc, s3, v230
	s_and_b64 vcc, vcc, s[54:55]
	s_nop 0
	v_permlane16_swap_b32_e32 v232, v234
	v_permlane16_swap_b32_e32 v233, v235
	s_and_saveexec_b64 s[0:1], vcc
	global_store_dwordx4 v231, v[232:235], s[12:13] offset:128
	s_mov_b64 exec, s[0:1]
